# adds: HGRN prep reads raw q/f/v words with ds_read2_b32 (6 LDS reads instead of 12 per half-step) and unpacks with v_perm_b32
# baseline (speedup 1.0000x reference)
; #define LAS __attribute__((address_space(3)))
; __device__ __forceinline__ int otid() { int t = threadIdx.x; asm volatile("" : "+v"(t)); return t; }
; template <bool DRY> __device__ __forceinline__ void hgrn_unit(LAS unsigned char* lds, int b, int h, int vs, int layer, bf16_t* Pm, const float* lbraw) {
;     using namespace hg;
;     const int tid = otid(), lane = tid & 63; const int wid = __builtin_amdgcn_readfirstlane(tid >> 6);
;     const size_t tok0 = (size_t)b * SEQ;
;     const int kl = lane & 15, tq = lane >> 4, kch = 16 * wid + kl;
;     (void)layer; (void)lbraw;
;     const bf16_t* qsrc = Pm + (tok0 + 4 * tq) * PW + PC_HQ + h * 128 + (kch & ~1);
;     const bf16_t* fsrc = Pm + (tok0 + 4 * tq) * PW + PC_HF + h * 128 + (kch & ~1);
;     const bool isv = tid < 128; const int vv = tid & 31, vtq = (tid >> 5) & 3;
;     const bf16_t* vsrc = Pm + (tok0 + 4 * vtq) * PW + PC_HI + h * 128 + vs * 32 + (vv & ~1);
;     constexpr int NSTEP = SEQ / 16;
;     for (int i = tid; i < SB / 4; i += NTHREADS) ((LAS unsigned*)(lds + OFF_S + SB))[i] = 0u;
;     Raw ra, rb;
;     load_raw(ra, qsrc, fsrc, vsrc, 0, isv);
;     prep(ra, lds, lane, kch, tq, isv, vv, vtq);
;     load_raw(ra, qsrc, fsrc, vsrc, 1, isv); load_raw(rb, qsrc, fsrc, vsrc, 2, isv);
;     f32x16 sacc = {};
;     const int c16 = lane & 15, kq = lane >> 4, r32 = lane & 31, hh = lane >> 5;
;     __syncthreads();
.LBB0_615:
	s_or_b64 exec, exec, s[6:7]
	s_ashr_i32 s6, s22, 4
	s_ashr_i32 s7, s6, 31
	v_bfe_u32 v9, v3, 4, 2
	s_lshl_b64 s[14:15], s[6:7], 11
	v_lshlrev_b32_e32 v8, 2, v9
	v_or_b32_e32 v0, s14, v8
	v_mov_b64_e32 v[4:5], s[4:5]
	v_bfe_u32 v12, v3, 5, 2
	s_ashr_i32 s28, s10, 6
	s_mov_b32 s65, s28
	v_mad_u64_u32 v[0:1], s[6:7], v0, s24, v[4:5]
	s_lshl_b32 s10, s22, 5
	v_lshl_or_b32 v6, v12, 2, s14
	s_and_b32 s6, s10, 0x180
	v_mad_u64_u32 v[4:5], s[8:9], v6, s24, v[4:5]
	v_and_b32_e32 v7, 15, v3
	s_lshl_b32 s34, s28, 4
	v_mad_i32_i24 v1, s15, v240, v1
	s_lshl_b32 s6, s6, 1
	s_mov_b32 s7, s29
	v_mad_i32_i24 v5, s15, v240, v5
	v_lshl_add_u64 v[0:1], v[0:1], 0, s[6:7]
	v_bitop3_b32 v10, s34, -2, v7 bitop3:0xc8
	v_lshl_add_u64 v[4:5], v[4:5], 0, s[6:7]
	s_and_b32 s7, s10, 0x60
	v_ashrrev_i32_e32 v11, 31, v10
	s_lshl_b32 s8, s7, 1
	s_mul_i32 s41, s14, 0x1d40
	s_add_u32 s38, s4, s41
	s_addc_u32 s39, s5, 0
	s_add_u32 s38, s38, s6
	s_addc_u32 s39, s39, 0
	s_add_u32 s38, s38, 0xd00
	s_addc_u32 s39, s39, 0
	s_mov_b32 s9, s29
	v_and_b32_e32 v6, 30, v3
	v_lshl_add_u64 v[0:1], v[10:11], 1, v[0:1]
	v_lshl_add_u64 v[4:5], v[4:5], 0, s[8:9]
	v_lshlrev_b32_e32 v10, 1, v6
	v_mov_b32_e32 v11, v2
	s_movk_i32 s7, 0x1000
	v_lshl_add_u64 v[4:5], v[4:5], 0, v[10:11]
	v_add_co_u32_e32 v10, vcc, s7, v0
	v_cmp_eq_u32_e64 s[50:51], 3, v9
	s_nop 0
	v_addc_co_u32_e32 v11, vcc, 0, v1, vcc
	v_add_co_u32_e32 v14, vcc, s7, v4
	s_movk_i32 s7, 0x2000
	s_nop 0
	v_addc_co_u32_e32 v15, vcc, 0, v5, vcc
	v_add_co_u32_e32 v16, vcc, s7, v0
	s_movk_i32 s7, 0x3000
	s_nop 0
	v_addc_co_u32_e32 v17, vcc, 0, v1, vcc
	v_add_co_u32_e32 v18, vcc, s7, v4
	s_movk_i32 s7, 0x4000
	s_nop 0
	v_addc_co_u32_e32 v19, vcc, 0, v5, vcc
	v_add_co_u32_e32 v20, vcc, s7, v0
	s_nop 1
	v_addc_co_u32_e32 v21, vcc, 0, v1, vcc
	s_nop 0
	s_nop 0
	s_nop 0
	s_nop 0
	v_add_co_u32_e32 v10, vcc, s7, v4
	s_movk_i32 s7, 0x6000
	s_nop 0
	v_addc_co_u32_e32 v11, vcc, 0, v5, vcc
	v_add_co_u32_e32 v10, vcc, s7, v0
	s_nop 1
	v_addc_co_u32_e32 v11, vcc, 0, v1, vcc
	v_add_co_u32_e32 v18, vcc, s7, v4
	s_movk_i32 s7, 0x440
	s_nop 0
	v_addc_co_u32_e32 v19, vcc, 0, v5, vcc
	s_nop 0
	v_and_b32_e32 v19, 1, v3
	v_cmp_eq_u32_e64 s[44:45], 0, v19
	v_and_b32_e32 v11, 63, v3
	v_cmp_gt_u32_e64 s[46:47], 16, v11
	v_cmp_lt_u32_e64 s[48:49], 31, v11
	v_or_b32_e32 v10, s34, v7
	v_lshl_add_u32 v36, v10, 1, 0
	v_mad_u32_u24 v42, v9, s7, v36
	v_bfe_u32 v140, v234, 4, 2
	v_mul_u32_u24_e32 v136, 0x440, v140
	v_lshrrev_b32_e32 v140, 6, v234
	v_and_b32_e32 v141, 15, v234
	v_lshl_or_b32 v140, v140, 4, v141
	v_lshrrev_b32_e32 v140, 1, v140
	v_lshl_add_u32 v136, v140, 2, v136
	v_add_u32_e32 v136, 0xd400, v136
	v_bfe_i32 v145, v234, 4, 1
	v_and_b32_e32 v151, 1, v234
	v_mov_b32_e32 v152, 0x2020000
	v_mul_lo_u32 v151, v151, v152
	v_add_u32_e32 v151, 0x1000c0c, v151
	v_and_b32_e32 v144, 1, v234
	v_lshl_add_u32 v144, v144, 1, v136
	v_bfe_u32 v140, v234, 5, 2
	v_and_b32_e32 v141, 31, v234
	v_lshrrev_b32_e32 v141, 1, v141
	v_lshlrev_b32_e32 v141, 2, v141
	v_lshl_add_u32 v137, v140, 8, v141
	v_add_u32_e32 v137, 0xf600, v137
	v_and_b32_e32 v140, 63, v234
	v_lshrrev_b32_e32 v141, 4, v140
	v_lshrrev_b32_e32 v142, 6, v234
	v_and_b32_e32 v143, 3, v142
	v_lshl_add_u32 v141, v143, 2, v141
	v_mul_u32_u24_e32 v138, 0x1d40, v141
	v_and_b32_e32 v141, 15, v140
	v_lshl_add_u32 v138, v141, 4, v138
	v_lshrrev_b32_e32 v142, 2, v142
	v_lshl_add_u32 v138, v142, 10, v138
	v_lshrrev_b32_e32 v141, 2, v140
	v_mul_u32_u24_e32 v139, 0x1d40, v141
	v_and_b32_e32 v141, 3, v140
	v_lshl_add_u32 v139, v141, 4, v139
	v_add_u32_e32 v139, 0x800, v139
	v_add_u32_e32 v139, s8, v139
	s_mul_i32 s64, s65, 0x440
	s_add_i32 s64, s64, 0xd400
	s_mov_b64 s[42:43], s[38:39]
	s_cmp_lg_u32 s65, 7
	s_cbranch_scc1 .Lhg_pro_nov
	s_add_i32 m0, s64, 0
	s_nop 0
	global_load_lds_dwordx4 v138, s[42:43]
	s_mov_b32 m0, 0xf600
	s_nop 0
	global_load_lds_dwordx4 v139, s[42:43]
	s_add_u32 s42, s42, 0x1d400
	s_addc_u32 s43, s43, 0
	s_add_i32 m0, s64, 9792
	s_nop 0
	global_load_lds_dwordx4 v138, s[42:43]
	s_mov_b32 m0, 0x11c40
	s_nop 0
	global_load_lds_dwordx4 v139, s[42:43]
	s_add_u32 s42, s42, 0x1d400
	s_addc_u32 s43, s43, 0
	s_add_i32 m0, s64, 19584
	s_nop 0
	global_load_lds_dwordx4 v138, s[42:43]
	s_mov_b32 m0, 0x14280
	s_nop 0
	global_load_lds_dwordx4 v139, s[42:43]
	s_add_u32 s42, s42, 0x1d400
	s_addc_u32 s43, s43, 0
	s_add_i32 m0, s64, 29376
	s_nop 0
	global_load_lds_dwordx4 v138, s[42:43]
	s_mov_b32 m0, 0x168c0
	s_nop 0
	global_load_lds_dwordx4 v139, s[42:43]
	s_waitcnt vmcnt(4)
	s_branch .Lhg_pro_done

; #define LAS __attribute__((address_space(3)))
; __device__ __forceinline__ unsigned cvtpk(float lo, float hi) { f32x2_t v = {lo, hi}; bf16x2_t b = __builtin_convertvector(v, bf16x2_t); return __builtin_bit_cast(unsigned, b); }
; __device__ __forceinline__ void prep(const Raw& Rin, LAS unsigned char* buf, int lane, int kch, int tq, bool isv, int vv, int vtq) {
;     Raw R = Rin; const bool kodd = kch & 1, vodd = vv & 1;
; #pragma unroll
;     for (int i = 0; i < 4; ++i) { asm volatile("" : "+v"(R.q[i])); asm volatile("" : "+v"(R.f[i])); asm volatile("" : "+v"(R.v[i])); }
;     float qv[4], kk[4], c[4]; float run = 0.f;
; #pragma unroll
;     for (int i = 0; i < 4; ++i) {
;         qv[i] = __uint_as_float(kodd ? (R.q[i] & 0xffff0000u) : (R.q[i] << 16));
;         const float l2 = __uint_as_float(kodd ? (R.f[i] & 0xffff0000u) : (R.f[i] << 16));
;         kk[i] = 1.f - __builtin_amdgcn_exp2f(l2);
;         run += l2; c[i] = run;
;     }
;     const float p1 = __shfl(run, (lane - 16) & 63), p2 = __shfl(run, (lane - 32) & 63), p3 = __shfl(run, (lane - 48) & 63);
;     const float off = (tq >= 1 ? p1 : 0.f) + (tq >= 2 ? p2 : 0.f) + (tq >= 3 ? p3 : 0.f);
;     const float btot = __shfl(off + run, 48 + (lane & 15));
;     unsigned short kf[4];
; #pragma unroll
;     for (int i = 0; i < 4; ++i) {
;         const float bt = off + c[i];
;         const float qf = qv[i] * __builtin_amdgcn_exp2f(bt), kfv = kk[i] * __builtin_amdgcn_exp2f(-bt);
;         const unsigned pk = cvtpk(qf, kfv);
;         *(LAS unsigned short*)(buf + OFF_QF + (4 * tq + i) * STR + kch * 2) = (unsigned short)(pk & 0xffffu);
;         kf[i] = (unsigned short)(pk >> 16);
;         *(LAS unsigned short*)(buf + OFF_KF + (4 * tq + i) * STR + kch * 2) = kf[i];
;     }
;     *(LAS u32x2*)(buf + OFF_KFT + kch * 32 + tq * 8) = (u32x2){(unsigned)kf[0] | ((unsigned)kf[1] << 16), (unsigned)kf[2] | ((unsigned)kf[3] << 16)};
;     if (tq == 0) *(LAS float*)(buf + OFF_D + kch * 4) = __builtin_amdgcn_exp2f(btot);
;     if (isv) { unsigned v0 = vodd ? R.v[0] >> 16 : R.v[0] & 0xffffu, v1 = vodd ? R.v[1] >> 16 : R.v[1] & 0xffffu, v2 = vodd ? R.v[2] >> 16 : R.v[2] & 0xffffu, v3 = vodd ? R.v[3] >> 16 : R.v[3] & 0xffffu;
;         *(LAS u32x2*)(buf + OFF_VT + vv * 32 + vtq * 8) = (u32x2){v0 | (v1 << 16), v2 | (v3 << 16)}; }
; }
.Lhg_nov_a:
	s_add_i32 s41, s7, 1
	s_and_b32 s41, s41, 3
	s_mul_i32 s41, s41, 9792
	v_add_u32_e32 v140, s41, v136
	v_add_u32_e32 v141, s41, v137
	v_add_u32_e32 v153, 0x1100, v140
	ds_read2_b32 v[156:157], v153 offset1:64
	ds_read2_b32 v[158:159], v153 offset0:128 offset1:192
	ds_read2_b32 v[160:161], v140 offset1:64
	ds_read2_b32 v[162:163], v140 offset0:128 offset1:192
	ds_read2_b32 v[40:41], v141 offset1:16
	ds_read2_b32 v[164:165], v141 offset0:32 offset1:48
	s_waitcnt lgkmcnt(4)
	v_perm_b32 v0, v156, v156, v151
	v_perm_b32 v1, v157, v157, v151
	v_perm_b32 v3, v158, v158, v151
	v_perm_b32 v56, v159, v159, v151
	v_exp_f32_e32 v81, v0
	v_exp_f32_e32 v83, v1
	v_exp_f32_e32 v87, v3
	v_exp_f32_e32 v54, v56
	v_add_f32_e32 v1, v0, v1
	v_add_f32_e32 v3, v1, v3
	v_add_f32_e32 v63, v3, v56
	v_mov_b32_e32 v146, v63
	v_mov_b32_e32 v147, v63
	v_sub_f32_e32 v81, 1.0, v81
	v_sub_f32_e32 v83, 1.0, v83
	v_permlane16_swap_b32_e32 v146, v147
	v_sub_f32_e32 v87, 1.0, v87
	v_add_f32_e32 v148, v146, v147
	v_mov_b32_e32 v149, v148
	v_and_b32_e32 v150, v146, v145
	s_nop 0
	v_permlane32_swap_b32_e32 v148, v149
	v_cndmask_b32_e64 v52, 0, v148, s[48:49]
	v_add_f32_e32 v52, v52, v150
	s_waitcnt lgkmcnt(0)
	v_perm_b32 v78, v160, v160, v151
	v_perm_b32 v62, v161, v161, v151
	v_perm_b32 v84, v162, v162, v151
	v_perm_b32 v88, v163, v163, v151
	v_add_f32_e32 v0, v0, v52
	v_exp_f32_e32 v80, v0
	v_exp_f32_e64 v79, -v0
	v_add_f32_e32 v1, v1, v52
	v_sub_f32_e32 v91, 1.0, v54
	v_add_f32_e32 v54, v63, v52
	v_exp_f32_e32 v82, v1
	v_exp_f32_e64 v63, -v1
	v_add_f32_e32 v3, v3, v52
	v_pk_mul_f32 v[78:79], v[80:81], v[78:79]
	v_exp_f32_e32 v86, v3
	v_exp_f32_e64 v85, -v3
	v_cvt_pk_bf16_f32 v56, v78, v79
	v_exp_f32_e32 v90, v54
	v_exp_f32_e64 v89, -v54
	v_add_u32_e32 v69, v26, v43
	v_pk_mul_f32 v[62:63], v[82:83], v[62:63]
	v_add_f32_e32 v0, v148, v149
	ds_write_b16_d16_hi v69, v56 offset:18688
	v_cvt_pk_bf16_f32 v1, v62, v63
	v_pk_mul_f32 v[62:63], v[86:87], v[84:85]
	ds_write_b16_d16_hi v69, v1 offset:18960
	v_cvt_pk_bf16_f32 v3, v62, v63
	v_pk_mul_f32 v[78:79], v[90:91], v[88:89]
	ds_write_b16 v69, v1 offset:14608
	v_perm_b32 v62, v1, v56, s17
	v_cvt_pk_bf16_f32 v1, v78, v79
	ds_write_b16_d16_hi v69, v3 offset:19232
	ds_write_b16 v69, v1 offset:15152
	v_lshrrev_b32_e32 v52, 16, v1
	v_perm_b32 v63, v1, v3, s17
	v_add_u32_e32 v1, v27, v37
	ds_write_b16 v69, v56 offset:14336
	ds_write_b16 v69, v3 offset:14880
	ds_write_b16 v69, v52 offset:19504
	ds_write_b64 v1, v[62:63] offset:23040
	s_and_saveexec_b64 s[14:15], s[46:47]
	s_cbranch_execz .LBB0_627
	s_waitcnt lgkmcnt(9)
	v_exp_f32_e32 v0, v0
	v_add_u32_e32 v1, v27, v45
	ds_write_b32 v1, v0 offset:28160
.LBB0_627:
	s_or_b64 exec, exec, s[14:15]
	s_and_saveexec_b64 s[14:15], s[52:53]
	s_cbranch_execz .LBB0_629
	s_mov_b64 vcc, s[44:45]
	s_waitcnt lgkmcnt(9)
	v_cndmask_b32_sdwa v0, v40, v40, vcc dst_sel:DWORD dst_unused:UNUSED_PAD src0_sel:WORD_1 src1_sel:WORD_0
	v_cndmask_b32_sdwa v1, v41, v41, vcc dst_sel:DWORD dst_unused:UNUSED_PAD src0_sel:WORD_1 src1_sel:DWORD
	v_cndmask_b32_sdwa v3, v164, v164, vcc dst_sel:DWORD dst_unused:UNUSED_PAD src0_sel:WORD_1 src1_sel:WORD_0
	v_cndmask_b32_sdwa v40, v165, v165, vcc dst_sel:DWORD dst_unused:UNUSED_PAD src0_sel:WORD_1 src1_sel:DWORD
	v_lshl_or_b32 v0, v1, 16, v0
	v_lshl_or_b32 v1, v40, 16, v3
	v_add_u32_e32 v3, v46, v39
	ds_write_b64 v3, v[0:1] offset:27136

; #define LAS __attribute__((address_space(3)))
; __device__ __forceinline__ unsigned cvtpk(float lo, float hi) { f32x2_t v = {lo, hi}; bf16x2_t b = __builtin_convertvector(v, bf16x2_t); return __builtin_bit_cast(unsigned, b); }
; __device__ __forceinline__ void prep(const Raw& Rin, LAS unsigned char* buf, int lane, int kch, int tq, bool isv, int vv, int vtq) {
;     Raw R = Rin; const bool kodd = kch & 1, vodd = vv & 1;
; #pragma unroll
;     for (int i = 0; i < 4; ++i) { asm volatile("" : "+v"(R.q[i])); asm volatile("" : "+v"(R.f[i])); asm volatile("" : "+v"(R.v[i])); }
;     float qv[4], kk[4], c[4]; float run = 0.f;
; #pragma unroll
;     for (int i = 0; i < 4; ++i) {
;         qv[i] = __uint_as_float(kodd ? (R.q[i] & 0xffff0000u) : (R.q[i] << 16));
;         const float l2 = __uint_as_float(kodd ? (R.f[i] & 0xffff0000u) : (R.f[i] << 16));
;         kk[i] = 1.f - __builtin_amdgcn_exp2f(l2);
;         run += l2; c[i] = run;
;     }
;     const float p1 = __shfl(run, (lane - 16) & 63), p2 = __shfl(run, (lane - 32) & 63), p3 = __shfl(run, (lane - 48) & 63);
;     const float off = (tq >= 1 ? p1 : 0.f) + (tq >= 2 ? p2 : 0.f) + (tq >= 3 ? p3 : 0.f);
;     const float btot = __shfl(off + run, 48 + (lane & 15));
;     unsigned short kf[4];
; #pragma unroll
;     for (int i = 0; i < 4; ++i) {
;         const float bt = off + c[i];
;         const float qf = qv[i] * __builtin_amdgcn_exp2f(bt), kfv = kk[i] * __builtin_amdgcn_exp2f(-bt);
;         const unsigned pk = cvtpk(qf, kfv);
;         *(LAS unsigned short*)(buf + OFF_QF + (4 * tq + i) * STR + kch * 2) = (unsigned short)(pk & 0xffffu);
;         kf[i] = (unsigned short)(pk >> 16);
;         *(LAS unsigned short*)(buf + OFF_KF + (4 * tq + i) * STR + kch * 2) = kf[i];
;     }
;     *(LAS u32x2*)(buf + OFF_KFT + kch * 32 + tq * 8) = (u32x2){(unsigned)kf[0] | ((unsigned)kf[1] << 16), (unsigned)kf[2] | ((unsigned)kf[3] << 16)};
;     if (tq == 0) *(LAS float*)(buf + OFF_D + kch * 4) = __builtin_amdgcn_exp2f(btot);
;     if (isv) { unsigned v0 = vodd ? R.v[0] >> 16 : R.v[0] & 0xffffu, v1 = vodd ? R.v[1] >> 16 : R.v[1] & 0xffffu, v2 = vodd ? R.v[2] >> 16 : R.v[2] & 0xffffu, v3 = vodd ? R.v[3] >> 16 : R.v[3] & 0xffffu;
;         *(LAS u32x2*)(buf + OFF_VT + vv * 32 + vtq * 8) = (u32x2){v0 | (v1 << 16), v2 | (v3 << 16)}; }
; }
.Lhg_nov_b:
	s_add_i32 s41, s7, 2
	s_and_b32 s41, s41, 3
	s_mul_i32 s41, s41, 9792
	v_add_u32_e32 v140, s41, v136
	v_add_u32_e32 v141, s41, v137
	v_add_u32_e32 v153, 0x1100, v140
	ds_read2_b32 v[156:157], v153 offset1:64
	ds_read2_b32 v[158:159], v153 offset0:128 offset1:192
	ds_read2_b32 v[160:161], v140 offset1:64
	ds_read2_b32 v[162:163], v140 offset0:128 offset1:192
	ds_read2_b32 v[166:167], v141 offset1:16
	ds_read2_b32 v[168:169], v141 offset0:32 offset1:48
	s_waitcnt lgkmcnt(4)
	v_perm_b32 v0, v156, v156, v151
	v_perm_b32 v1, v157, v157, v151
	v_perm_b32 v3, v158, v158, v151
	v_perm_b32 v72, v159, v159, v151
	v_exp_f32_e32 v81, v0
	v_exp_f32_e32 v85, v1
	v_exp_f32_e32 v87, v3
	v_exp_f32_e32 v68, v72
	v_add_f32_e32 v1, v0, v1
	v_add_f32_e32 v3, v1, v3
	v_add_f32_e32 v75, v3, v72
	v_mov_b32_e32 v146, v75
	v_mov_b32_e32 v147, v75
	v_sub_f32_e32 v81, 1.0, v81
	v_sub_f32_e32 v85, 1.0, v85
	v_permlane16_swap_b32_e32 v146, v147
	v_sub_f32_e32 v87, 1.0, v87
	v_add_f32_e32 v148, v146, v147
	v_mov_b32_e32 v149, v148
	v_and_b32_e32 v150, v146, v145
	s_nop 0
	v_permlane32_swap_b32_e32 v148, v149
	v_cndmask_b32_e64 v72, 0, v148, s[48:49]
	v_add_f32_e32 v72, v72, v150
	s_waitcnt lgkmcnt(0)
	v_perm_b32 v66, v160, v160, v151
	v_perm_b32 v82, v161, v161, v151
	v_perm_b32 v74, v162, v162, v151
	v_perm_b32 v76, v163, v163, v151
	v_add_f32_e32 v0, v0, v72
	v_exp_f32_e32 v80, v0
	v_exp_f32_e64 v67, -v0
	v_add_f32_e32 v1, v1, v72
	v_exp_f32_e32 v84, v1
	v_exp_f32_e64 v83, -v1
	v_sub_f32_e32 v89, 1.0, v68
	v_add_f32_e32 v68, v75, v72
	v_add_f32_e32 v3, v3, v72
	v_pk_mul_f32 v[66:67], v[80:81], v[66:67]
	v_exp_f32_e32 v86, v3
	v_exp_f32_e64 v75, -v3
	v_exp_f32_e32 v88, v68
	v_exp_f32_e64 v77, -v68
	v_cvt_pk_bf16_f32 v79, v66, v67
	v_add_f32_e32 v0, v148, v149
	v_add_u32_e32 v80, v36, v43
	v_pk_mul_f32 v[66:67], v[84:85], v[82:83]
	ds_write_b16_d16_hi v80, v79 offset:4352
	v_cvt_pk_bf16_f32 v1, v66, v67
	v_pk_mul_f32 v[66:67], v[86:87], v[74:75]
	v_pk_mul_f32 v[74:75], v[88:89], v[76:77]
	ds_write_b16 v80, v1 offset:272
	ds_write_b16_d16_hi v80, v1 offset:4624
	v_cvt_pk_bf16_f32 v3, v66, v67
	v_perm_b32 v66, v1, v79, s17
	v_cvt_pk_bf16_f32 v1, v74, v75
	v_lshrrev_b32_e32 v68, 16, v1
	ds_write_b16 v80, v79
	ds_write_b16 v80, v3 offset:544
	ds_write_b16_d16_hi v80, v3 offset:4896
	ds_write_b16 v80, v1 offset:816
	v_perm_b32 v67, v1, v3, s17
	ds_write_b16 v80, v68 offset:5168
	ds_write_b64 v38, v[66:67] offset:8704
	s_and_saveexec_b64 s[14:15], s[46:47]
	s_cbranch_execz .LBB0_638
	s_waitcnt lgkmcnt(9)
	v_exp_f32_e32 v0, v0
	v_add_u32_e32 v1, v27, v45
	ds_write_b32 v1, v0 offset:13824
.LBB0_638:
	s_or_b64 exec, exec, s[14:15]
	s_and_saveexec_b64 s[14:15], s[52:53]
	s_cbranch_execz .LBB0_640
	s_mov_b64 vcc, s[44:45]
	s_waitcnt lgkmcnt(9)
	v_cndmask_b32_sdwa v0, v166, v166, vcc dst_sel:DWORD dst_unused:UNUSED_PAD src0_sel:WORD_1 src1_sel:WORD_0
	v_cndmask_b32_sdwa v1, v167, v167, vcc dst_sel:DWORD dst_unused:UNUSED_PAD src0_sel:WORD_1 src1_sel:DWORD
	v_cndmask_b32_sdwa v3, v168, v168, vcc dst_sel:DWORD dst_unused:UNUSED_PAD src0_sel:WORD_1 src1_sel:WORD_0
	v_cndmask_b32_sdwa v42, v169, v169, vcc dst_sel:DWORD dst_unused:UNUSED_PAD src0_sel:WORD_1 src1_sel:DWORD
	v_lshl_or_b32 v0, v1, 16, v0
	v_lshl_or_b32 v1, v42, 16, v3
	v_add_u32_e32 v3, v46, v39
	ds_write_b64 v3, v[0:1] offset:12800
